# xattn PV loop: software-pipelined transposed V reads (ring of 8 quads, 6 steps ahead) instead of read-wait-mfma
# speedup vs baseline: 1.0907x; 1.0126x over previous
; __device__ __forceinline__ v4i16_t vtr(lds_cptr p) { return __builtin_amdgcn_ds_read_tr16_b64_v4i16((LAS v4i16_t*)p); }
; __device__ __forceinline__ void glds16(const void* gsrc, LAS unsigned char* dst_uniform) { __builtin_amdgcn_global_load_lds((const unsigned*)gsrc, (LAS unsigned*)dst_uniform, 16, 0, 0); }
; #define ATT_SYNC() do { asm volatile("s_waitcnt vmcnt(0) lgkmcnt(0)" ::: "memory"); __syncthreads(); } while (0)
; __device__ __forceinline__ void xattn_unit(LAS unsigned char* lds, const bf16_t* Qx, const bf16_t* KV, int li, int b, int h, int qb, bf16_t* XO, const int tid) {
;     ...
;     const bf16_t* Vb = Kb + 1024;
; #pragma unroll 4
;     for (int ii = 0; ii < 16; ++ii) { const int i = wid * 16 + ii, d0 = i >> 4, ks = i & 15, key = 16 * ks + 8 * hi + ((lane >> 2) & 7), cc = lane & 3;
;         glds16(Vb + (size_t)key * 8192 + 32 * d0 + 8 * cc, lds + i * 1024); }
;     ATT_SYNC();
;     const lds_cptr vb = (lds_cptr)lds + ((lane >> 4) & 1) * 32 + (lane & 3) * 8 + (4 * hi + ((lane & 15) >> 2)) * 64;
;     bf16_t* orow = XO + tok * 1024 + h * 256;
; #pragma unroll 1
;     for (int d0 = 0; d0 < 8; ++d0) { f32x16 acc = {};
; #pragma unroll
;         for (int ks = 0; ks < 16; ++ks) { const v4i16_t lo = vtr(vb + d0 * 16384 + ks * 1024), hh = vtr(vb + d0 * 16384 + ks * 1024 + 512);
;             const bf16x8 vf = {lo[0], lo[1], lo[2], lo[3], hh[0], hh[1], hh[2], hh[3]};
;             acc = __builtin_amdgcn_mfma_f32_32x32x16_bf16(vf, pf[ks], acc, 0, 0, 0); }
;         const u32x4 none[2] = {}; store_ot<false>(acc, inv, orow + 32 * d0, hi, 0.f, 0.f, none); }
.LBB0_434:
	v_lshl_add_u64 v[8:9], v[6:7], 0, s[0:1]
	s_mov_b32 m0, s24
	s_nop 0
	global_load_lds_dwordx4 v[8:9], off
	v_lshl_add_u64 v[8:9], v[4:5], 0, s[0:1]
	s_add_i32 m0, s24, 0x400
	s_nop 0
	global_load_lds_dwordx4 v[8:9], off
	v_lshl_add_u64 v[8:9], v[2:3], 0, s[0:1]
	s_add_i32 m0, s24, 0x800
	s_nop 0
	global_load_lds_dwordx4 v[8:9], off
	v_lshl_add_u64 v[8:9], v[0:1], 0, s[0:1]
	s_add_i32 m0, s24, 0xc00
	s_add_u32 s0, s0, 0x100000
	global_load_lds_dwordx4 v[8:9], off
	s_addc_u32 s1, s1, 0
	s_addk_i32 s24, 0x1000
	s_cmp_eq_u32 s0, 0x400000
	s_cbranch_scc0 .LBB0_434
	v_add_f32_e32 v0, v80, v81
	v_rcp_f32_e32 v82, v0
	s_waitcnt vmcnt(0) lgkmcnt(0)
	v_lshl_add_u64 v[0:1], v[200:201], 1, s[10:11]
	v_lshl_add_u64 v[0:1], s[12:13], 1, v[0:1]
	v_mov_b32_e32 v199, v209
	v_lshl_add_u64 v[80:81], v[0:1], 0, v[198:199]
	s_mov_b32 s0, 0
	s_waitcnt vmcnt(0) lgkmcnt(0)
	s_barrier
	v_add_u32_e32 v83, s0, v250
	ds_read_b64_tr_b16 v[84:85], v83
	ds_read_b64_tr_b16 v[86:87], v83 offset:512
	ds_read_b64_tr_b16 v[128:129], v83 offset:1024
	ds_read_b64_tr_b16 v[130:131], v83 offset:1536
	ds_read_b64_tr_b16 v[132:133], v83 offset:2048
	ds_read_b64_tr_b16 v[134:135], v83 offset:2560
	ds_read_b64_tr_b16 v[136:137], v83 offset:3072
	ds_read_b64_tr_b16 v[138:139], v83 offset:3584
	ds_read_b64_tr_b16 v[140:141], v83 offset:4096
	ds_read_b64_tr_b16 v[142:143], v83 offset:4608
	ds_read_b64_tr_b16 v[144:145], v83 offset:5120
	ds_read_b64_tr_b16 v[146:147], v83 offset:5632
.LBB0_436:
	v_add_u32_e32 v83, s0, v250
	s_addk_i32 s0, 0x4000
	s_cmp_lg_u32 s0, 0x20000
	s_waitcnt lgkmcnt(10)
	v_mfma_f32_32x32x16_bf16 v[0:15], v[84:87], v[16:19], 0
	ds_read_b64_tr_b16 v[148:149], v83 offset:6144
	ds_read_b64_tr_b16 v[150:151], v83 offset:6656
	s_waitcnt lgkmcnt(10)
	v_mfma_f32_32x32x16_bf16 v[0:15], v[128:131], v[20:23], v[0:15]
	ds_read_b64_tr_b16 v[152:153], v83 offset:7168
	ds_read_b64_tr_b16 v[154:155], v83 offset:7680
	s_waitcnt lgkmcnt(10)
	v_mfma_f32_32x32x16_bf16 v[0:15], v[132:135], v[24:27], v[0:15]
	ds_read_b64_tr_b16 v[84:85], v83 offset:8192
	ds_read_b64_tr_b16 v[86:87], v83 offset:8704
	s_waitcnt lgkmcnt(10)
	v_mfma_f32_32x32x16_bf16 v[0:15], v[136:139], v[28:31], v[0:15]
	ds_read_b64_tr_b16 v[128:129], v83 offset:9216
	ds_read_b64_tr_b16 v[130:131], v83 offset:9728
	s_waitcnt lgkmcnt(10)
	v_mfma_f32_32x32x16_bf16 v[0:15], v[140:143], v[32:35], v[0:15]
	ds_read_b64_tr_b16 v[132:133], v83 offset:10240
	ds_read_b64_tr_b16 v[134:135], v83 offset:10752
	s_waitcnt lgkmcnt(10)
	v_mfma_f32_32x32x16_bf16 v[0:15], v[144:147], v[36:39], v[0:15]
	ds_read_b64_tr_b16 v[136:137], v83 offset:11264
	ds_read_b64_tr_b16 v[138:139], v83 offset:11776
	s_waitcnt lgkmcnt(10)
	v_mfma_f32_32x32x16_bf16 v[0:15], v[148:151], v[40:43], v[0:15]
	ds_read_b64_tr_b16 v[140:141], v83 offset:12288
	ds_read_b64_tr_b16 v[142:143], v83 offset:12800
	s_waitcnt lgkmcnt(10)
	v_mfma_f32_32x32x16_bf16 v[0:15], v[152:155], v[44:47], v[0:15]
	ds_read_b64_tr_b16 v[144:145], v83 offset:13312
	ds_read_b64_tr_b16 v[146:147], v83 offset:13824
	s_waitcnt lgkmcnt(10)
	v_mfma_f32_32x32x16_bf16 v[0:15], v[84:87], v[48:51], v[0:15]
	ds_read_b64_tr_b16 v[148:149], v83 offset:14336
	ds_read_b64_tr_b16 v[150:151], v83 offset:14848
	s_waitcnt lgkmcnt(10)
	v_mfma_f32_32x32x16_bf16 v[0:15], v[128:131], v[52:55], v[0:15]
	ds_read_b64_tr_b16 v[152:153], v83 offset:15360
	ds_read_b64_tr_b16 v[154:155], v83 offset:15872
	s_waitcnt lgkmcnt(10)
	v_mfma_f32_32x32x16_bf16 v[0:15], v[132:135], v[56:59], v[0:15]
	ds_read_b64_tr_b16 v[84:85], v83 offset:16384
	ds_read_b64_tr_b16 v[86:87], v83 offset:16896
	s_waitcnt lgkmcnt(10)
	v_mfma_f32_32x32x16_bf16 v[0:15], v[136:139], v[60:63], v[0:15]
	ds_read_b64_tr_b16 v[128:129], v83 offset:17408
	ds_read_b64_tr_b16 v[130:131], v83 offset:17920
	s_waitcnt lgkmcnt(10)
	v_mfma_f32_32x32x16_bf16 v[0:15], v[140:143], v[64:67], v[0:15]
	ds_read_b64_tr_b16 v[132:133], v83 offset:18432
	ds_read_b64_tr_b16 v[134:135], v83 offset:18944
	s_waitcnt lgkmcnt(10)
	v_mfma_f32_32x32x16_bf16 v[0:15], v[144:147], v[68:71], v[0:15]
	ds_read_b64_tr_b16 v[136:137], v83 offset:19456
	ds_read_b64_tr_b16 v[138:139], v83 offset:19968
	s_waitcnt lgkmcnt(10)
	v_mfma_f32_32x32x16_bf16 v[0:15], v[148:151], v[72:75], v[0:15]
	ds_read_b64_tr_b16 v[140:141], v83 offset:20480
	ds_read_b64_tr_b16 v[142:143], v83 offset:20992
	s_waitcnt lgkmcnt(10)
	v_mfma_f32_32x32x16_bf16 v[0:15], v[152:155], v[76:79], v[0:15]
	ds_read_b64_tr_b16 v[144:145], v83 offset:21504
	ds_read_b64_tr_b16 v[146:147], v83 offset:22016
	s_nop 11
	v_mul_f32_e32 v0, v82, v0
	v_mul_f32_e32 v1, v82, v1
	v_cvt_pk_bf16_f32 v0, v0, v1
	v_mul_f32_e32 v1, v82, v2
	v_mul_f32_e32 v2, v82, v3
	v_cvt_pk_bf16_f32 v1, v1, v2
	v_mul_f32_e32 v2, v82, v4
	v_mul_f32_e32 v3, v82, v5
	v_cvt_pk_bf16_f32 v2, v2, v3
	v_mul_f32_e32 v3, v82, v6
	v_mul_f32_e32 v4, v82, v7
	v_cvt_pk_bf16_f32 v3, v3, v4
	v_mul_f32_e32 v4, v82, v8
	v_mul_f32_e32 v5, v82, v9
	v_cvt_pk_bf16_f32 v4, v4, v5
	v_mul_f32_e32 v5, v82, v10
	v_mul_f32_e32 v6, v82, v11
	v_cvt_pk_bf16_f32 v5, v5, v6
	v_mul_f32_e32 v6, v82, v12
	v_mul_f32_e32 v7, v82, v13
	v_cvt_pk_bf16_f32 v6, v6, v7
	v_mul_f32_e32 v7, v82, v14
	v_mul_f32_e32 v8, v82, v15
	v_cvt_pk_bf16_f32 v7, v7, v8
	v_permlane32_swap_b32_e32 v0, v2
	v_permlane32_swap_b32_e32 v1, v3
	v_permlane32_swap_b32_e32 v4, v6
	v_permlane32_swap_b32_e32 v5, v7
	global_store_dwordx4 v[80:81], v[0:3], off
	global_store_dwordx4 v[80:81], v[4:7], off offset:32
	v_lshl_add_u64 v[80:81], v[80:81], 0, 64
	s_cbranch_scc1 .LBB0_436
	s_waitcnt vmcnt(0) lgkmcnt(0)
	s_add_i32 s16, s16, 1
	s_mov_b64 s[0:1], 0
	s_barrier
	s_branch .LBB0_427
